# epilogue wait-state pruning: removed 82 leftover s_nop 0 between s_mov s48 and global_store_short in ffn_in epilogues (vcc hazard pad no longer needed after v_lshl_add_u64 address compaction)
# baseline (speedup 1.0000x reference)
; DEV float silu(float x) { return x * sigm(x); }
; template <bool RES, class Epi>
; DEV void gemm_tile_x(const bf16_t* A0, int lda0, const bf16_t* A1, int lda1, int ksplit,
;                      const bf16_t* Bt, int ldb, int K, char* smem, const float* resb, Epi epi) {
;     ...
;       for (int r8 = 0; r8 < 8; ++r8) {
;         const int r = rh * 8 + r8;
;         const int ru = mi * 32 + (r & 3) + 8 * (r >> 2);
;         if (RES) epi(ru, rl, col, acc[mi][0][r], acc[mi][1][r], x0[r8], x1[r8]);
;         else epi(ru, rl, col, acc[mi][0][r], acc[mi][1][r], 0.f, 0.f);
;         if ((r8 & 3) == 3) __builtin_amdgcn_sched_barrier(0);
; DEV void phase_ffn_in(const Params& p, const bf16_t* wt, char* smem) {
;     ...
;               [&](int ru, int rl, int c, float v0, float v1) {
;                 (hb + ru * DFF)[(unsigned)(rl * DFF + (c >> 6) * 32 + (c & 31))] = f2bf(silu(v0) * v1);
;               });
.LBB0_174:
	s_waitcnt vmcnt(5)
	v_mul_f32_e32 v128, 0xbfb8aa3b, v112
	v_exp_f32_e32 v128, v128
	s_lshl_b32 s52, s52, 6
	s_mul_hi_u32 s54, s48, 0x160000
	s_mul_i32 s48, s48, 0x160000
	v_add_f32_e32 v128, 1.0, v128
	v_rcp_f32_e32 v128, v128
	s_ashr_i32 s53, s52, 31
	s_add_u32 s48, s84, s48
	s_addc_u32 s54, s85, s54
	s_lshl_b64 s[52:53], s[52:53], 1
	s_add_u32 s52, s48, s52
	v_mul_f32_e32 v112, v112, v128
	s_addc_u32 s53, s54, s53
	v_mul_f32_e32 v96, v96, v112
	v_cvt_pk_bf16_f32 v96, v96, s0
	v_lshl_add_u64 v[128:129], v[182:183], 1, s[52:53]
	global_store_short v[128:129], v96, off
	v_mul_f32_e32 v96, 0xbfb8aa3b, v113
	v_exp_f32_e32 v96, v96
	s_movk_i32 s48, 0x1000
	v_add_f32_e32 v96, 1.0, v96
	v_rcp_f32_e32 v96, v96
	s_nop 0
	v_mul_f32_e32 v96, v113, v96
	v_mul_f32_e32 v96, v97, v96
	v_cvt_pk_bf16_f32 v112, v96, s0
	v_lshl_add_u64 v[96:97], v[128:129], 0, s[48:49]
	s_movk_i32 s48, 0x2000
	global_store_short v[96:97], v112, off offset:1536
	v_mul_f32_e32 v96, 0xbfb8aa3b, v114
	v_exp_f32_e32 v96, v96
	s_nop 0
	v_add_f32_e32 v96, 1.0, v96
	v_rcp_f32_e32 v96, v96
	s_nop 0
	v_mul_f32_e32 v96, v114, v96
	v_mul_f32_e32 v96, v98, v96
	v_cvt_pk_bf16_f32 v98, v96, s0
	v_lshl_add_u64 v[96:97], v[128:129], 0, s[48:49]
	s_movk_i32 s48, 0x4000
	global_store_short v[96:97], v98, off offset:3072
	v_mul_f32_e32 v96, 0xbfb8aa3b, v115
	v_exp_f32_e32 v96, v96
	s_nop 0
	v_add_f32_e32 v96, 1.0, v96
	v_rcp_f32_e32 v96, v96
	s_nop 0
	v_mul_f32_e32 v96, v115, v96
	v_mul_f32_e32 v96, v99, v96
	v_cvt_pk_bf16_f32 v98, v96, s0
	v_lshl_add_u64 v[96:97], v[128:129], 0, s[48:49]
	global_store_short v[96:97], v98, off offset:512
	v_mul_f32_e32 v96, 0xbfb8aa3b, v116
	v_exp_f32_e32 v96, v96
	s_mov_b32 s48, 0xb000
	v_add_f32_e32 v96, 1.0, v96
	v_rcp_f32_e32 v96, v96
	s_nop 0
	v_mul_f32_e32 v96, v116, v96
	v_mul_f32_e32 v96, v100, v96
	v_cvt_pk_bf16_f32 v98, v96, s0
	v_lshl_add_u64 v[96:97], v[128:129], 0, s[48:49]
	s_mov_b32 s48, 0xc000
	global_store_short v[96:97], v98, off
	v_mul_f32_e32 v96, 0xbfb8aa3b, v117
	v_exp_f32_e32 v96, v96
	s_nop 0
	v_add_f32_e32 v96, 1.0, v96
	v_rcp_f32_e32 v96, v96
	s_nop 0
	v_mul_f32_e32 v96, v117, v96
	v_mul_f32_e32 v96, v101, v96
	v_cvt_pk_bf16_f32 v98, v96, s0
	v_lshl_add_u64 v[96:97], v[128:129], 0, s[48:49]
	s_mov_b32 s48, 0xd000
	global_store_short v[96:97], v98, off offset:1536
	v_mul_f32_e32 v96, 0xbfb8aa3b, v118
	v_exp_f32_e32 v96, v96
	s_nop 0
	v_add_f32_e32 v96, 1.0, v96
	v_rcp_f32_e32 v96, v96
	s_nop 0
	v_mul_f32_e32 v96, v118, v96
	v_mul_f32_e32 v96, v102, v96
	v_cvt_pk_bf16_f32 v98, v96, s0
	v_lshl_add_u64 v[96:97], v[128:129], 0, s[48:49]
	s_mov_b32 s48, 0xf000
	global_store_short v[96:97], v98, off offset:3072
	v_mul_f32_e32 v96, 0xbfb8aa3b, v119
	v_exp_f32_e32 v96, v96
	s_nop 0
	v_add_f32_e32 v96, 1.0, v96
	v_rcp_f32_e32 v96, v96
	s_nop 0
	v_mul_f32_e32 v96, v119, v96
	v_mul_f32_e32 v96, v103, v96
	v_cvt_pk_bf16_f32 v98, v96, s0
	v_lshl_add_u64 v[96:97], v[128:129], 0, s[48:49]
	global_store_short v[96:97], v98, off offset:512
	v_mul_f32_e32 v96, 0xbfb8aa3b, v120
	v_exp_f32_e32 v96, v96
	s_mov_b32 s48, 0x16000
	v_add_f32_e32 v96, 1.0, v96
	v_rcp_f32_e32 v96, v96
	s_nop 0
	v_mul_f32_e32 v96, v120, v96
	v_mul_f32_e32 v96, v104, v96
	v_cvt_pk_bf16_f32 v98, v96, s0
	v_lshl_add_u64 v[96:97], v[128:129], 0, s[48:49]
	s_mov_b32 s48, 0x17000
	global_store_short v[96:97], v98, off
	v_mul_f32_e32 v96, 0xbfb8aa3b, v121
	v_exp_f32_e32 v96, v96
	s_nop 0
	v_add_f32_e32 v96, 1.0, v96
	v_rcp_f32_e32 v96, v96
	s_nop 0
	v_mul_f32_e32 v96, v121, v96
	v_mul_f32_e32 v96, v105, v96
	v_cvt_pk_bf16_f32 v98, v96, s0
	v_lshl_add_u64 v[96:97], v[128:129], 0, s[48:49]
	s_mov_b32 s48, 0x18000
	global_store_short v[96:97], v98, off offset:1536
	v_mul_f32_e32 v96, 0xbfb8aa3b, v122
	v_exp_f32_e32 v96, v96
	s_nop 0
	v_add_f32_e32 v96, 1.0, v96
	v_rcp_f32_e32 v96, v96
	s_nop 0
	v_mul_f32_e32 v96, v122, v96
	v_mul_f32_e32 v96, v106, v96
	v_cvt_pk_bf16_f32 v98, v96, s0
	v_lshl_add_u64 v[96:97], v[128:129], 0, s[48:49]
	s_mov_b32 s48, 0x1a000
	global_store_short v[96:97], v98, off offset:3072
	v_mul_f32_e32 v96, 0xbfb8aa3b, v123
	v_exp_f32_e32 v96, v96
	s_nop 0
	v_add_f32_e32 v96, 1.0, v96
	v_rcp_f32_e32 v96, v96
	s_nop 0
	v_mul_f32_e32 v96, v123, v96
	v_mul_f32_e32 v96, v107, v96
	v_cvt_pk_bf16_f32 v98, v96, s0
	v_lshl_add_u64 v[96:97], v[128:129], 0, s[48:49]
	global_store_short v[96:97], v98, off offset:512
	v_mul_f32_e32 v96, 0xbfb8aa3b, v124
	v_exp_f32_e32 v96, v96
	s_mov_b32 s48, 0x21000
	v_add_f32_e32 v96, 1.0, v96
	v_rcp_f32_e32 v96, v96
	s_nop 0
	v_mul_f32_e32 v96, v124, v96
	v_mul_f32_e32 v96, v108, v96
	v_cvt_pk_bf16_f32 v98, v96, s0
	v_lshl_add_u64 v[96:97], v[128:129], 0, s[48:49]
	s_mov_b32 s48, 0x22000
	global_store_short v[96:97], v98, off
	v_mul_f32_e32 v96, 0xbfb8aa3b, v125
	v_exp_f32_e32 v96, v96
	s_nop 0
	v_add_f32_e32 v96, 1.0, v96
	v_rcp_f32_e32 v96, v96
	s_nop 0
	v_mul_f32_e32 v96, v125, v96
	v_mul_f32_e32 v96, v109, v96
	v_cvt_pk_bf16_f32 v98, v96, s0
	v_lshl_add_u64 v[96:97], v[128:129], 0, s[48:49]
	s_mov_b32 s48, 0x23000
	global_store_short v[96:97], v98, off offset:1536
	v_mul_f32_e32 v96, 0xbfb8aa3b, v126
	v_exp_f32_e32 v96, v96
	s_nop 0
	v_add_f32_e32 v96, 1.0, v96
	v_rcp_f32_e32 v96, v96
	s_nop 0
	v_mul_f32_e32 v96, v126, v96
	v_mul_f32_e32 v96, v110, v96
	v_cvt_pk_bf16_f32 v98, v96, s0
	v_lshl_add_u64 v[96:97], v[128:129], 0, s[48:49]
	s_mov_b32 s48, 0x25000
	global_store_short v[96:97], v98, off offset:3072
	v_mul_f32_e32 v96, 0xbfb8aa3b, v127
	v_exp_f32_e32 v96, v96
	s_nop 0
	v_add_f32_e32 v96, 1.0, v96
	v_rcp_f32_e32 v96, v96
	s_nop 0
	v_mul_f32_e32 v96, v127, v96
	v_mul_f32_e32 v96, v111, v96
	v_cvt_pk_bf16_f32 v98, v96, s0
; DEV float silu(float x) { return x * sigm(x); }
; template <bool RES, class Epi>
; DEV void gemm_tile_x(const bf16_t* A0, int lda0, const bf16_t* A1, int lda1, int ksplit,
;                      const bf16_t* Bt, int ldb, int K, char* smem, const float* resb, Epi epi) {
;     ...
;       for (int r8 = 0; r8 < 8; ++r8) {
;         const int r = rh * 8 + r8;
;         const int ru = mi * 32 + (r & 3) + 8 * (r >> 2);
;         if (RES) epi(ru, rl, col, acc[mi][0][r], acc[mi][1][r], x0[r8], x1[r8]);
;         else epi(ru, rl, col, acc[mi][0][r], acc[mi][1][r], 0.f, 0.f);
;         if ((r8 & 3) == 3) __builtin_amdgcn_sched_barrier(0);
; DEV void phase_ffn_in(const Params& p, const bf16_t* wt, char* smem) {
;     ...
;               [&](int ru, int rl, int c, float v0, float v1) {
;                 (hb + ru * DFF)[(unsigned)(rl * DFF + (c >> 6) * 32 + (c & 31))] = f2bf(silu(v0) * v1);
;               });
	v_lshl_add_u64 v[96:97], v[128:129], 0, s[48:49]
	global_store_short v[96:97], v98, off offset:512
	v_mul_f32_e32 v96, 0xbfb8aa3b, v80
	v_exp_f32_e32 v96, v96
	s_mov_b32 s48, 0x2c000
	v_add_f32_e32 v96, 1.0, v96
	v_rcp_f32_e32 v96, v96
	s_nop 0
	v_mul_f32_e32 v80, v80, v96
	v_mul_f32_e32 v64, v64, v80
	v_lshl_add_u64 v[96:97], v[128:129], 0, s[48:49]
	v_cvt_pk_bf16_f32 v64, v64, s0
	s_nop 0
	global_store_short v[96:97], v64, off
	v_mul_f32_e32 v64, 0xbfb8aa3b, v81
	v_exp_f32_e32 v64, v64
	s_mov_b32 s48, 0x2d000
	v_add_f32_e32 v64, 1.0, v64
	v_rcp_f32_e32 v64, v64
	s_nop 0
	v_mul_f32_e32 v64, v81, v64
	v_mul_f32_e32 v64, v65, v64
	v_cvt_pk_bf16_f32 v80, v64, s0
	v_lshl_add_u64 v[64:65], v[128:129], 0, s[48:49]
	s_mov_b32 s48, 0x2e000
	global_store_short v[64:65], v80, off offset:1536
	v_mul_f32_e32 v64, 0xbfb8aa3b, v82
	v_exp_f32_e32 v64, v64
	s_nop 0
	v_add_f32_e32 v64, 1.0, v64
	v_rcp_f32_e32 v64, v64
	s_nop 0
	v_mul_f32_e32 v64, v82, v64
	v_mul_f32_e32 v64, v66, v64
	v_cvt_pk_bf16_f32 v66, v64, s0
	v_lshl_add_u64 v[64:65], v[128:129], 0, s[48:49]
	s_mov_b32 s48, 0x30000
	global_store_short v[64:65], v66, off offset:3072
	v_mul_f32_e32 v64, 0xbfb8aa3b, v83
	v_exp_f32_e32 v64, v64
	s_nop 0
	v_add_f32_e32 v64, 1.0, v64
	v_rcp_f32_e32 v64, v64
	s_nop 0
	v_mul_f32_e32 v64, v83, v64
	v_mul_f32_e32 v64, v67, v64
	v_cvt_pk_bf16_f32 v66, v64, s0
	v_lshl_add_u64 v[64:65], v[128:129], 0, s[48:49]
	global_store_short v[64:65], v66, off offset:512
	v_mul_f32_e32 v64, 0xbfb8aa3b, v84
	v_exp_f32_e32 v64, v64
	s_mov_b32 s48, 0x37000
	v_add_f32_e32 v64, 1.0, v64
	v_rcp_f32_e32 v64, v64
	s_nop 0
	v_mul_f32_e32 v64, v84, v64
	v_mul_f32_e32 v64, v68, v64
	v_cvt_pk_bf16_f32 v66, v64, s0
	v_lshl_add_u64 v[64:65], v[128:129], 0, s[48:49]
	s_mov_b32 s48, 0x38000
	global_store_short v[64:65], v66, off
	v_mul_f32_e32 v64, 0xbfb8aa3b, v85
	v_exp_f32_e32 v64, v64
	s_nop 0
	v_add_f32_e32 v64, 1.0, v64
	v_rcp_f32_e32 v64, v64
	s_nop 0
	v_mul_f32_e32 v64, v85, v64
	v_mul_f32_e32 v64, v69, v64
	v_cvt_pk_bf16_f32 v66, v64, s0
	v_lshl_add_u64 v[64:65], v[128:129], 0, s[48:49]
	s_mov_b32 s48, 0x39000
	global_store_short v[64:65], v66, off offset:1536
	v_mul_f32_e32 v64, 0xbfb8aa3b, v86
	v_exp_f32_e32 v64, v64
	s_nop 0
	v_add_f32_e32 v64, 1.0, v64
	v_rcp_f32_e32 v64, v64
	s_nop 0
	v_mul_f32_e32 v64, v86, v64
	v_mul_f32_e32 v64, v70, v64
	v_cvt_pk_bf16_f32 v66, v64, s0
	v_lshl_add_u64 v[64:65], v[128:129], 0, s[48:49]
	s_mov_b32 s48, 0x3b000
	global_store_short v[64:65], v66, off offset:3072
	v_mul_f32_e32 v64, 0xbfb8aa3b, v87
	v_exp_f32_e32 v64, v64
	s_nop 0
	v_add_f32_e32 v64, 1.0, v64
	v_rcp_f32_e32 v64, v64
	s_nop 0
	v_mul_f32_e32 v64, v87, v64
	v_mul_f32_e32 v64, v71, v64
	v_cvt_pk_bf16_f32 v66, v64, s0
	v_lshl_add_u64 v[64:65], v[128:129], 0, s[48:49]
	global_store_short v[64:65], v66, off offset:512
	v_mul_f32_e32 v64, 0xbfb8aa3b, v88
	v_exp_f32_e32 v64, v64
	s_mov_b32 s48, 0x42000
	v_add_f32_e32 v64, 1.0, v64
	v_rcp_f32_e32 v64, v64
	s_nop 0
	v_mul_f32_e32 v64, v88, v64
	v_mul_f32_e32 v64, v72, v64
	v_cvt_pk_bf16_f32 v66, v64, s0
	v_lshl_add_u64 v[64:65], v[128:129], 0, s[48:49]
	s_mov_b32 s48, 0x43000
	global_store_short v[64:65], v66, off
	v_mul_f32_e32 v64, 0xbfb8aa3b, v89
	v_exp_f32_e32 v64, v64
	s_nop 0
	v_add_f32_e32 v64, 1.0, v64
	v_rcp_f32_e32 v64, v64
	s_nop 0
	v_mul_f32_e32 v64, v89, v64
	v_mul_f32_e32 v64, v73, v64
	v_cvt_pk_bf16_f32 v66, v64, s0
	v_lshl_add_u64 v[64:65], v[128:129], 0, s[48:49]
	s_mov_b32 s48, 0x44000
	global_store_short v[64:65], v66, off offset:1536
	v_mul_f32_e32 v64, 0xbfb8aa3b, v90
	v_exp_f32_e32 v64, v64
	s_nop 0
	v_add_f32_e32 v64, 1.0, v64
	v_rcp_f32_e32 v64, v64
	s_nop 0
	v_mul_f32_e32 v64, v90, v64
	v_mul_f32_e32 v64, v74, v64
	v_cvt_pk_bf16_f32 v66, v64, s0
	v_lshl_add_u64 v[64:65], v[128:129], 0, s[48:49]
	s_mov_b32 s48, 0x46000
	global_store_short v[64:65], v66, off offset:3072
	v_mul_f32_e32 v64, 0xbfb8aa3b, v91
	v_exp_f32_e32 v64, v64
	s_nop 0
	v_add_f32_e32 v64, 1.0, v64
	v_rcp_f32_e32 v64, v64
	s_nop 0
	v_mul_f32_e32 v64, v91, v64
	v_mul_f32_e32 v64, v75, v64
	v_cvt_pk_bf16_f32 v66, v64, s0
	v_lshl_add_u64 v[64:65], v[128:129], 0, s[48:49]
	global_store_short v[64:65], v66, off offset:512
	v_mul_f32_e32 v64, 0xbfb8aa3b, v92
	v_exp_f32_e32 v64, v64
	s_mov_b32 s48, 0x4d000
	v_add_f32_e32 v64, 1.0, v64
	v_rcp_f32_e32 v64, v64
	s_nop 0
	v_mul_f32_e32 v64, v92, v64
	v_mul_f32_e32 v64, v76, v64
	v_cvt_pk_bf16_f32 v66, v64, s0
	v_lshl_add_u64 v[64:65], v[128:129], 0, s[48:49]
	s_mov_b32 s48, 0x4e000
	global_store_short v[64:65], v66, off
	v_mul_f32_e32 v64, 0xbfb8aa3b, v93
	v_exp_f32_e32 v64, v64
	s_nop 0
	v_add_f32_e32 v64, 1.0, v64
	v_rcp_f32_e32 v64, v64
	s_nop 0
	v_mul_f32_e32 v64, v93, v64
	v_mul_f32_e32 v64, v77, v64
	v_cvt_pk_bf16_f32 v66, v64, s0
	v_lshl_add_u64 v[64:65], v[128:129], 0, s[48:49]
	s_mov_b32 s48, 0x4f000
	global_store_short v[64:65], v66, off offset:1536
	v_mul_f32_e32 v64, 0xbfb8aa3b, v94
	v_exp_f32_e32 v64, v64
	s_nop 0
	v_add_f32_e32 v64, 1.0, v64
	v_rcp_f32_e32 v64, v64
	s_nop 0
	v_mul_f32_e32 v64, v94, v64
	v_mul_f32_e32 v64, v78, v64
	v_cvt_pk_bf16_f32 v66, v64, s0
	v_lshl_add_u64 v[64:65], v[128:129], 0, s[48:49]
	s_mov_b32 s48, 0x51000
	global_store_short v[64:65], v66, off offset:3072
	v_mul_f32_e32 v64, 0xbfb8aa3b, v95
	v_exp_f32_e32 v64, v64
	s_nop 0
	v_add_f32_e32 v64, 1.0, v64
	v_rcp_f32_e32 v64, v64
	s_nop 0
	v_mul_f32_e32 v64, v95, v64
	v_mul_f32_e32 v64, v79, v64
	v_cvt_pk_bf16_f32 v66, v64, s0
	v_lshl_add_u64 v[64:65], v[128:129], 0, s[48:49]
	global_store_short v[64:65], v66, off offset:512
	v_mul_f32_e32 v64, 0xbfb8aa3b, v48
	v_exp_f32_e32 v64, v64
	s_mov_b32 s48, 0x58000
; DEV float silu(float x) { return x * sigm(x); }
; template <bool RES, class Epi>
; DEV void gemm_tile_x(const bf16_t* A0, int lda0, const bf16_t* A1, int lda1, int ksplit,
;                      const bf16_t* Bt, int ldb, int K, char* smem, const float* resb, Epi epi) {
;     ...
;       for (int r8 = 0; r8 < 8; ++r8) {
;         const int r = rh * 8 + r8;
;         const int ru = mi * 32 + (r & 3) + 8 * (r >> 2);
;         if (RES) epi(ru, rl, col, acc[mi][0][r], acc[mi][1][r], x0[r8], x1[r8]);
;         else epi(ru, rl, col, acc[mi][0][r], acc[mi][1][r], 0.f, 0.f);
;         if ((r8 & 3) == 3) __builtin_amdgcn_sched_barrier(0);
; DEV void phase_ffn_in(const Params& p, const bf16_t* wt, char* smem) {
;     ...
;               [&](int ru, int rl, int c, float v0, float v1) {
;                 (hb + ru * DFF)[(unsigned)(rl * DFF + (c >> 6) * 32 + (c & 31))] = f2bf(silu(v0) * v1);
;               });
	v_add_f32_e32 v64, 1.0, v64
	v_rcp_f32_e32 v64, v64
	s_nop 0
	v_mul_f32_e32 v48, v48, v64
	v_mul_f32_e32 v32, v32, v48
	v_lshl_add_u64 v[64:65], v[128:129], 0, s[48:49]
	v_cvt_pk_bf16_f32 v32, v32, s0
	s_nop 0
	global_store_short v[64:65], v32, off
	v_mul_f32_e32 v32, 0xbfb8aa3b, v49
	v_exp_f32_e32 v32, v32
	s_mov_b32 s48, 0x59000
	v_add_f32_e32 v32, 1.0, v32
	v_rcp_f32_e32 v32, v32
	s_nop 0
	v_mul_f32_e32 v32, v49, v32
	v_mul_f32_e32 v32, v33, v32
	v_cvt_pk_bf16_f32 v48, v32, s0
	v_lshl_add_u64 v[32:33], v[128:129], 0, s[48:49]
	s_mov_b32 s48, 0x5a000
	global_store_short v[32:33], v48, off offset:1536
	v_mul_f32_e32 v32, 0xbfb8aa3b, v50
	v_exp_f32_e32 v32, v32
	s_nop 0
	v_add_f32_e32 v32, 1.0, v32
	v_rcp_f32_e32 v32, v32
	s_nop 0
	v_mul_f32_e32 v32, v50, v32
	v_mul_f32_e32 v32, v34, v32
	v_cvt_pk_bf16_f32 v34, v32, s0
	v_lshl_add_u64 v[32:33], v[128:129], 0, s[48:49]
	s_mov_b32 s48, 0x5c000
	global_store_short v[32:33], v34, off offset:3072
	v_mul_f32_e32 v32, 0xbfb8aa3b, v51
	v_exp_f32_e32 v32, v32
	s_nop 0
	v_add_f32_e32 v32, 1.0, v32
	v_rcp_f32_e32 v32, v32
	s_nop 0
	v_mul_f32_e32 v32, v51, v32
	v_mul_f32_e32 v32, v35, v32
	v_cvt_pk_bf16_f32 v34, v32, s0
	v_lshl_add_u64 v[32:33], v[128:129], 0, s[48:49]
	global_store_short v[32:33], v34, off offset:512
	v_mul_f32_e32 v32, 0xbfb8aa3b, v52
	v_exp_f32_e32 v32, v32
	s_mov_b32 s48, 0x63000
	v_add_f32_e32 v32, 1.0, v32
	v_rcp_f32_e32 v32, v32
	s_nop 0
	v_mul_f32_e32 v32, v52, v32
	v_mul_f32_e32 v32, v36, v32
	v_cvt_pk_bf16_f32 v34, v32, s0
	v_lshl_add_u64 v[32:33], v[128:129], 0, s[48:49]
	s_mov_b32 s48, 0x64000
	global_store_short v[32:33], v34, off
	v_mul_f32_e32 v32, 0xbfb8aa3b, v53
	v_exp_f32_e32 v32, v32
	s_nop 0
	v_add_f32_e32 v32, 1.0, v32
	v_rcp_f32_e32 v32, v32
	s_nop 0
	v_mul_f32_e32 v32, v53, v32
	v_mul_f32_e32 v32, v37, v32
	v_cvt_pk_bf16_f32 v34, v32, s0
	v_lshl_add_u64 v[32:33], v[128:129], 0, s[48:49]
	s_mov_b32 s48, 0x65000
	global_store_short v[32:33], v34, off offset:1536
	v_mul_f32_e32 v32, 0xbfb8aa3b, v54
	v_exp_f32_e32 v32, v32
	s_nop 0
	v_add_f32_e32 v32, 1.0, v32
	v_rcp_f32_e32 v32, v32
	s_nop 0
	v_mul_f32_e32 v32, v54, v32
	v_mul_f32_e32 v32, v38, v32
	v_cvt_pk_bf16_f32 v34, v32, s0
	v_lshl_add_u64 v[32:33], v[128:129], 0, s[48:49]
	s_mov_b32 s48, 0x67000
	global_store_short v[32:33], v34, off offset:3072
	v_mul_f32_e32 v32, 0xbfb8aa3b, v55
	v_exp_f32_e32 v32, v32
	s_nop 0
	v_add_f32_e32 v32, 1.0, v32
	v_rcp_f32_e32 v32, v32
	s_nop 0
	v_mul_f32_e32 v32, v55, v32
	v_mul_f32_e32 v32, v39, v32
	v_cvt_pk_bf16_f32 v34, v32, s0
	v_lshl_add_u64 v[32:33], v[128:129], 0, s[48:49]
	global_store_short v[32:33], v34, off offset:512
	v_mul_f32_e32 v32, 0xbfb8aa3b, v56
	v_exp_f32_e32 v32, v32
	s_mov_b32 s48, 0x6e000
	v_add_f32_e32 v32, 1.0, v32
	v_rcp_f32_e32 v32, v32
	s_nop 0
	v_mul_f32_e32 v32, v56, v32
	v_mul_f32_e32 v32, v40, v32
	v_cvt_pk_bf16_f32 v34, v32, s0
	v_lshl_add_u64 v[32:33], v[128:129], 0, s[48:49]
	s_mov_b32 s48, 0x6f000
	global_store_short v[32:33], v34, off
	v_mul_f32_e32 v32, 0xbfb8aa3b, v57
	v_exp_f32_e32 v32, v32
	s_nop 0
	v_add_f32_e32 v32, 1.0, v32
	v_rcp_f32_e32 v32, v32
	s_nop 0
	v_mul_f32_e32 v32, v57, v32
	v_mul_f32_e32 v32, v41, v32
	v_cvt_pk_bf16_f32 v34, v32, s0
	v_lshl_add_u64 v[32:33], v[128:129], 0, s[48:49]
	s_mov_b32 s48, 0x70000
	global_store_short v[32:33], v34, off offset:1536
	v_mul_f32_e32 v32, 0xbfb8aa3b, v58
	v_exp_f32_e32 v32, v32
	s_nop 0
	v_add_f32_e32 v32, 1.0, v32
	v_rcp_f32_e32 v32, v32
	s_nop 0
	v_mul_f32_e32 v32, v58, v32
	v_mul_f32_e32 v32, v42, v32
	v_cvt_pk_bf16_f32 v34, v32, s0
	v_lshl_add_u64 v[32:33], v[128:129], 0, s[48:49]
	s_mov_b32 s48, 0x72000
	global_store_short v[32:33], v34, off offset:3072
	v_mul_f32_e32 v32, 0xbfb8aa3b, v59
	v_exp_f32_e32 v32, v32
	s_nop 0
	v_add_f32_e32 v32, 1.0, v32
	v_rcp_f32_e32 v32, v32
	s_nop 0
	v_mul_f32_e32 v32, v59, v32
	v_mul_f32_e32 v32, v43, v32
	v_cvt_pk_bf16_f32 v34, v32, s0
	v_lshl_add_u64 v[32:33], v[128:129], 0, s[48:49]
	global_store_short v[32:33], v34, off offset:512
	v_mul_f32_e32 v32, 0xbfb8aa3b, v60
	v_exp_f32_e32 v32, v32
	s_mov_b32 s48, 0x79000
	v_add_f32_e32 v32, 1.0, v32
	v_rcp_f32_e32 v32, v32
	s_nop 0
	v_mul_f32_e32 v32, v60, v32
	v_mul_f32_e32 v32, v44, v32
	v_cvt_pk_bf16_f32 v34, v32, s0
	v_lshl_add_u64 v[32:33], v[128:129], 0, s[48:49]
	s_mov_b32 s48, 0x7a000
	global_store_short v[32:33], v34, off
	v_mul_f32_e32 v32, 0xbfb8aa3b, v61
	v_exp_f32_e32 v32, v32
	s_nop 0
	v_add_f32_e32 v32, 1.0, v32
	v_rcp_f32_e32 v32, v32
	s_nop 0
	v_mul_f32_e32 v32, v61, v32
	v_mul_f32_e32 v32, v45, v32
	v_cvt_pk_bf16_f32 v34, v32, s0
	v_lshl_add_u64 v[32:33], v[128:129], 0, s[48:49]
	s_mov_b32 s48, 0x7b000
	global_store_short v[32:33], v34, off offset:1536
	v_mul_f32_e32 v32, 0xbfb8aa3b, v62
	v_exp_f32_e32 v32, v32
	s_nop 0
	v_add_f32_e32 v32, 1.0, v32
	v_rcp_f32_e32 v32, v32
	s_nop 0
	v_mul_f32_e32 v32, v62, v32
	v_mul_f32_e32 v32, v46, v32
	v_cvt_pk_bf16_f32 v34, v32, s0
	v_lshl_add_u64 v[32:33], v[128:129], 0, s[48:49]
	s_mov_b32 s48, 0x7d000
	global_store_short v[32:33], v34, off offset:3072
	v_mul_f32_e32 v32, 0xbfb8aa3b, v63
	v_exp_f32_e32 v32, v32
	s_nop 0
	v_add_f32_e32 v32, 1.0, v32
	v_rcp_f32_e32 v32, v32
	s_nop 0
	v_mul_f32_e32 v32, v63, v32
	v_mul_f32_e32 v32, v47, v32
	v_cvt_pk_bf16_f32 v34, v32, s0
	v_lshl_add_u64 v[32:33], v[128:129], 0, s[48:49]
; DEV float silu(float x) { return x * sigm(x); }
; DEV bool tile_map(int it, int nct, int& rt, int& ct) {
;   const int bpx = gridDim.x >> 3, xcd = blockIdx.x & 7, j = blockIdx.x >> 3;
;   const int q = j + it * bpx;
;   if (q >= 24 * nct) return false;
; DEV void phase_ffn_in(const Params& p, const bf16_t* wt, char* smem) {
;     ...
;               [&](int ru, int rl, int c, float v0, float v1) {
;                 (hb + ru * DFF)[(unsigned)(rl * DFF + (c >> 6) * 32 + (c & 31))] = f2bf(silu(v0) * v1);
;               });
	global_store_short v[32:33], v34, off offset:512
	v_mul_f32_e32 v32, 0xbfb8aa3b, v16
	v_exp_f32_e32 v32, v32
	s_mov_b32 s48, 0x84000
	v_add_f32_e32 v32, 1.0, v32
	v_rcp_f32_e32 v32, v32
	s_nop 0
	v_mul_f32_e32 v16, v16, v32
	v_mul_f32_e32 v0, v0, v16
	v_lshl_add_u64 v[32:33], v[128:129], 0, s[48:49]
	v_cvt_pk_bf16_f32 v0, v0, s0
	s_nop 0
	global_store_short v[32:33], v0, off
	v_mul_f32_e32 v0, 0xbfb8aa3b, v17
	v_exp_f32_e32 v0, v0
	s_mov_b32 s48, 0x85000
	v_add_f32_e32 v0, 1.0, v0
	v_rcp_f32_e32 v0, v0
	s_nop 0
	v_mul_f32_e32 v0, v17, v0
	v_mul_f32_e32 v0, v1, v0
	v_cvt_pk_bf16_f32 v16, v0, s0
	v_lshl_add_u64 v[0:1], v[128:129], 0, s[48:49]
	s_mov_b32 s48, 0x86000
	global_store_short v[0:1], v16, off offset:1536
	v_mul_f32_e32 v0, 0xbfb8aa3b, v18
	v_exp_f32_e32 v0, v0
	s_nop 0
	v_add_f32_e32 v0, 1.0, v0
	v_rcp_f32_e32 v0, v0
	s_nop 0
	v_mul_f32_e32 v0, v18, v0
	v_mul_f32_e32 v0, v2, v0
	v_cvt_pk_bf16_f32 v2, v0, s0
	v_lshl_add_u64 v[0:1], v[128:129], 0, s[48:49]
	s_mov_b32 s48, 0x88000
	global_store_short v[0:1], v2, off offset:3072
	v_mul_f32_e32 v0, 0xbfb8aa3b, v19
	v_exp_f32_e32 v0, v0
	s_nop 0
	v_add_f32_e32 v0, 1.0, v0
	v_rcp_f32_e32 v0, v0
	s_nop 0
	v_mul_f32_e32 v0, v19, v0
	v_mul_f32_e32 v0, v3, v0
	v_cvt_pk_bf16_f32 v2, v0, s0
	v_lshl_add_u64 v[0:1], v[128:129], 0, s[48:49]
	global_store_short v[0:1], v2, off offset:512
	v_mul_f32_e32 v0, 0xbfb8aa3b, v20
	v_exp_f32_e32 v0, v0
	s_mov_b32 s48, 0x8f000
	v_add_f32_e32 v0, 1.0, v0
	v_rcp_f32_e32 v0, v0
	s_nop 0
	v_mul_f32_e32 v0, v20, v0
	v_mul_f32_e32 v0, v4, v0
	v_cvt_pk_bf16_f32 v2, v0, s0
	v_lshl_add_u64 v[0:1], v[128:129], 0, s[48:49]
	s_mov_b32 s48, 0x90000
	global_store_short v[0:1], v2, off
	v_mul_f32_e32 v0, 0xbfb8aa3b, v21
	v_exp_f32_e32 v0, v0
	s_nop 0
	v_add_f32_e32 v0, 1.0, v0
	v_rcp_f32_e32 v0, v0
	s_nop 0
	v_mul_f32_e32 v0, v21, v0
	v_mul_f32_e32 v0, v5, v0
	v_cvt_pk_bf16_f32 v2, v0, s0
	v_lshl_add_u64 v[0:1], v[128:129], 0, s[48:49]
	s_mov_b32 s48, 0x91000
	global_store_short v[0:1], v2, off offset:1536
	v_mul_f32_e32 v0, 0xbfb8aa3b, v22
	v_exp_f32_e32 v0, v0
	s_nop 0
	v_add_f32_e32 v0, 1.0, v0
	v_rcp_f32_e32 v0, v0
	s_nop 0
	v_mul_f32_e32 v0, v22, v0
	v_mul_f32_e32 v0, v6, v0
	v_cvt_pk_bf16_f32 v2, v0, s0
	v_lshl_add_u64 v[0:1], v[128:129], 0, s[48:49]
	s_mov_b32 s48, 0x93000
	global_store_short v[0:1], v2, off offset:3072
	v_mul_f32_e32 v0, 0xbfb8aa3b, v23
	v_exp_f32_e32 v0, v0
	s_nop 0
	v_add_f32_e32 v0, 1.0, v0
	v_rcp_f32_e32 v0, v0
	s_nop 0
	v_mul_f32_e32 v0, v23, v0
	v_mul_f32_e32 v0, v7, v0
	v_cvt_pk_bf16_f32 v2, v0, s0
	v_lshl_add_u64 v[0:1], v[128:129], 0, s[48:49]
	global_store_short v[0:1], v2, off offset:512
	v_mul_f32_e32 v0, 0xbfb8aa3b, v24
	v_exp_f32_e32 v0, v0
	s_mov_b32 s48, 0x9a000
	v_add_f32_e32 v0, 1.0, v0
	v_rcp_f32_e32 v0, v0
	s_nop 0
	v_mul_f32_e32 v0, v24, v0
	v_mul_f32_e32 v0, v8, v0
	v_cvt_pk_bf16_f32 v2, v0, s0
	v_lshl_add_u64 v[0:1], v[128:129], 0, s[48:49]
	s_mov_b32 s48, 0x9b000
	global_store_short v[0:1], v2, off
	v_mul_f32_e32 v0, 0xbfb8aa3b, v25
	v_exp_f32_e32 v0, v0
	s_nop 0
	v_add_f32_e32 v0, 1.0, v0
	v_rcp_f32_e32 v0, v0
	s_nop 0
	v_mul_f32_e32 v0, v25, v0
	v_mul_f32_e32 v0, v9, v0
	v_cvt_pk_bf16_f32 v2, v0, s0
	v_lshl_add_u64 v[0:1], v[128:129], 0, s[48:49]
	s_mov_b32 s48, 0x9c000
	global_store_short v[0:1], v2, off offset:1536
	v_mul_f32_e32 v0, 0xbfb8aa3b, v26
	v_exp_f32_e32 v0, v0
	s_nop 0
	v_add_f32_e32 v0, 1.0, v0
	v_rcp_f32_e32 v0, v0
	s_nop 0
	v_mul_f32_e32 v0, v26, v0
	v_mul_f32_e32 v0, v10, v0
	v_cvt_pk_bf16_f32 v2, v0, s0
	v_lshl_add_u64 v[0:1], v[128:129], 0, s[48:49]
	s_mov_b32 s48, 0x9e000
	global_store_short v[0:1], v2, off offset:3072
	v_mul_f32_e32 v0, 0xbfb8aa3b, v27
	v_exp_f32_e32 v0, v0
	s_nop 0
	v_add_f32_e32 v0, 1.0, v0
	v_rcp_f32_e32 v0, v0
	s_nop 0
	v_mul_f32_e32 v0, v27, v0
	v_mul_f32_e32 v0, v11, v0
	v_cvt_pk_bf16_f32 v2, v0, s0
	v_lshl_add_u64 v[0:1], v[128:129], 0, s[48:49]
	global_store_short v[0:1], v2, off offset:512
	v_mul_f32_e32 v0, 0xbfb8aa3b, v28
	v_exp_f32_e32 v0, v0
	s_mov_b32 s48, 0xa5000
	v_add_f32_e32 v0, 1.0, v0
	v_rcp_f32_e32 v0, v0
	s_nop 0
	v_mul_f32_e32 v0, v28, v0
	v_mul_f32_e32 v0, v12, v0
	v_cvt_pk_bf16_f32 v2, v0, s0
	v_lshl_add_u64 v[0:1], v[128:129], 0, s[48:49]
	s_mov_b32 s48, 0xa6000
	global_store_short v[0:1], v2, off
	v_mul_f32_e32 v0, 0xbfb8aa3b, v29
	v_exp_f32_e32 v0, v0
	s_nop 0
	v_add_f32_e32 v0, 1.0, v0
	v_rcp_f32_e32 v0, v0
	s_nop 0
	v_mul_f32_e32 v0, v29, v0
	v_mul_f32_e32 v0, v13, v0
	v_cvt_pk_bf16_f32 v2, v0, s0
	v_lshl_add_u64 v[0:1], v[128:129], 0, s[48:49]
	s_mov_b32 s48, 0xa7000
	global_store_short v[0:1], v2, off offset:1536
	v_mul_f32_e32 v0, 0xbfb8aa3b, v30
	v_exp_f32_e32 v0, v0
	s_nop 0
	v_add_f32_e32 v0, 1.0, v0
	v_rcp_f32_e32 v0, v0
	s_nop 0
	v_mul_f32_e32 v0, v30, v0
	v_mul_f32_e32 v0, v14, v0
	v_cvt_pk_bf16_f32 v2, v0, s0
	v_lshl_add_u64 v[0:1], v[128:129], 0, s[48:49]
	global_store_short v[0:1], v2, off offset:3072
	v_mul_f32_e32 v0, 0xbfb8aa3b, v31
	v_exp_f32_e32 v0, v0
	s_nop 0
	v_add_f32_e32 v0, 1.0, v0
	v_rcp_f32_e32 v0, v0
	s_nop 0
	v_mul_f32_e32 v0, v31, v0
	v_mul_f32_e32 v0, v15, v0
	v_cvt_pk_bf16_f32 v2, v0, s0
	v_add_co_u32_e32 v0, vcc, 0xa9000, v128
	s_nop 1
	v_addc_co_u32_e32 v1, vcc, 0, v129, vcc
	global_store_short v[0:1], v2, off offset:512
	s_add_i32 s58, s58, 1
	s_mul_i32 s48, s58, s86
	s_add_i32 s48, s48, s87
	s_cmpk_lt_u32 s48, 0x420
	s_cbranch_scc0 .LBB0_183

; DEV float silu(float x) { return x * sigm(x); }
; template <bool RES, class Epi>
; DEV void gemm_tile_x(const bf16_t* A0, int lda0, const bf16_t* A1, int lda1, int ksplit,
;                      const bf16_t* Bt, int ldb, int K, char* smem, const float* resb, Epi epi) {
;     ...
;       for (int r8 = 0; r8 < 8; ++r8) {
;         const int r = rh * 8 + r8;
;         const int ru = mi * 32 + (r & 3) + 8 * (r >> 2);
;         if (RES) epi(ru, rl, col, acc[mi][0][r], acc[mi][1][r], x0[r8], x1[r8]);
;         else epi(ru, rl, col, acc[mi][0][r], acc[mi][1][r], 0.f, 0.f);
;         if ((r8 & 3) == 3) __builtin_amdgcn_sched_barrier(0);
; DEV void phase_ffn_in(const Params& p, const bf16_t* wt, char* smem) {
;     ...
;               [&](int ru, int rl, int c, float v0, float v1) {
;                 (hb + ru * DFF)[(unsigned)(rl * DFF + (c >> 6) * 32 + (c & 31))] = f2bf(silu(v0) * v1);
;               });
.LBB0_3200:
	s_waitcnt vmcnt(5)
	v_mul_f32_e32 v128, 0xbfb8aa3b, v112
	v_exp_f32_e32 v128, v128
	v_mul_f32_e32 v129, 0xbfb8aa3b, v113
	v_exp_f32_e32 v129, v129
	s_lshl_b32 s52, s52, 6
	v_add_f32_e32 v128, 1.0, v128
	v_rcp_f32_e32 v128, v128
	s_mul_hi_u32 s54, s48, 0x160000
	s_mul_i32 s48, s48, 0x160000
	s_ashr_i32 s53, s52, 31
	v_mul_f32_e32 v112, v112, v128
	s_add_u32 s48, s70, s48
	v_mul_f32_e32 v96, v96, v112
	v_add_f32_e32 v112, 1.0, v129
	s_addc_u32 s54, s71, s54
	s_lshl_b64 s[52:53], s[52:53], 1
	v_rcp_f32_e32 v112, v112
	s_add_u32 s52, s48, s52
	s_addc_u32 s53, s54, s53
	v_cvt_pk_bf16_f32 v96, v96, s0
	v_lshl_add_u64 v[128:129], v[182:183], 1, s[52:53]
	global_store_short v[128:129], v96, off
	v_mul_f32_e32 v96, v113, v112
	v_mul_f32_e32 v112, 0xbfb8aa3b, v114
	v_exp_f32_e32 v112, v112
	v_mul_f32_e32 v96, v97, v96
	v_cvt_pk_bf16_f32 v113, v96, s0
	s_movk_i32 s48, 0x1000
	v_add_f32_e32 v96, 1.0, v112
	v_rcp_f32_e32 v112, v96
	v_lshl_add_u64 v[96:97], v[128:129], 0, s[48:49]
	s_movk_i32 s48, 0x2000
	global_store_short v[96:97], v113, off offset:1536
	v_mul_f32_e32 v97, 0xbfb8aa3b, v115
	v_exp_f32_e32 v97, v97
	v_mul_f32_e32 v96, v114, v112
	v_mul_f32_e32 v96, v98, v96
	v_cvt_pk_bf16_f32 v98, v96, s0
	v_add_f32_e32 v96, 1.0, v97
	v_rcp_f32_e32 v112, v96
	v_lshl_add_u64 v[96:97], v[128:129], 0, s[48:49]
	s_movk_i32 s48, 0x4000
	global_store_short v[96:97], v98, off offset:3072
	v_mul_f32_e32 v96, v115, v112
	v_mul_f32_e32 v96, v99, v96
	v_cvt_pk_bf16_f32 v98, v96, s0
	v_lshl_add_u64 v[96:97], v[128:129], 0, s[48:49]
	global_store_short v[96:97], v98, off offset:512
	v_mul_f32_e32 v96, 0xbfb8aa3b, v116
	v_exp_f32_e32 v96, v96
	v_mul_f32_e32 v97, 0xbfb8aa3b, v117
	v_exp_f32_e32 v97, v97
	s_mov_b32 s48, 0xb000
	v_add_f32_e32 v96, 1.0, v96
	v_rcp_f32_e32 v96, v96
	v_add_f32_e32 v97, 1.0, v97
	v_rcp_f32_e32 v98, v97
	v_mul_f32_e32 v96, v116, v96
	v_mul_f32_e32 v96, v100, v96
	v_cvt_pk_bf16_f32 v99, v96, s0
	v_lshl_add_u64 v[96:97], v[128:129], 0, s[48:49]
	s_mov_b32 s48, 0xc000
	global_store_short v[96:97], v99, off
	v_mul_f32_e32 v97, 0xbfb8aa3b, v118
	v_exp_f32_e32 v97, v97
	v_mul_f32_e32 v96, v117, v98
	v_mul_f32_e32 v96, v101, v96
	v_cvt_pk_bf16_f32 v98, v96, s0
	v_add_f32_e32 v96, 1.0, v97
	v_rcp_f32_e32 v99, v96
	v_lshl_add_u64 v[96:97], v[128:129], 0, s[48:49]
	s_mov_b32 s48, 0xd000
	global_store_short v[96:97], v98, off offset:1536
	v_mul_f32_e32 v97, 0xbfb8aa3b, v119
	v_exp_f32_e32 v97, v97
	v_mul_f32_e32 v96, v118, v99
	v_mul_f32_e32 v96, v102, v96
	v_cvt_pk_bf16_f32 v98, v96, s0
	v_add_f32_e32 v96, 1.0, v97
	v_rcp_f32_e32 v99, v96
	v_lshl_add_u64 v[96:97], v[128:129], 0, s[48:49]
	s_mov_b32 s48, 0xf000
	global_store_short v[96:97], v98, off offset:3072
	v_mul_f32_e32 v96, v119, v99
	v_mul_f32_e32 v96, v103, v96
	v_cvt_pk_bf16_f32 v98, v96, s0
	v_lshl_add_u64 v[96:97], v[128:129], 0, s[48:49]
	global_store_short v[96:97], v98, off offset:512
	v_mul_f32_e32 v96, 0xbfb8aa3b, v120
	v_exp_f32_e32 v96, v96
	v_mul_f32_e32 v97, 0xbfb8aa3b, v121
	v_exp_f32_e32 v97, v97
	s_mov_b32 s48, 0x16000
	v_add_f32_e32 v96, 1.0, v96
	v_rcp_f32_e32 v96, v96
	v_add_f32_e32 v97, 1.0, v97
	v_rcp_f32_e32 v98, v97
	v_mul_f32_e32 v96, v120, v96
	v_mul_f32_e32 v96, v104, v96
	v_cvt_pk_bf16_f32 v99, v96, s0
	v_lshl_add_u64 v[96:97], v[128:129], 0, s[48:49]
	s_mov_b32 s48, 0x17000
	global_store_short v[96:97], v99, off
	v_mul_f32_e32 v97, 0xbfb8aa3b, v122
	v_exp_f32_e32 v97, v97
	v_mul_f32_e32 v96, v121, v98
	v_mul_f32_e32 v96, v105, v96
	v_cvt_pk_bf16_f32 v98, v96, s0
	v_add_f32_e32 v96, 1.0, v97
	v_rcp_f32_e32 v99, v96
	v_lshl_add_u64 v[96:97], v[128:129], 0, s[48:49]
	s_mov_b32 s48, 0x18000
	global_store_short v[96:97], v98, off offset:1536
	v_mul_f32_e32 v97, 0xbfb8aa3b, v123
	v_exp_f32_e32 v97, v97
	v_mul_f32_e32 v96, v122, v99
	v_mul_f32_e32 v96, v106, v96
	v_cvt_pk_bf16_f32 v98, v96, s0
	v_add_f32_e32 v96, 1.0, v97
	v_rcp_f32_e32 v99, v96
	v_lshl_add_u64 v[96:97], v[128:129], 0, s[48:49]
	s_mov_b32 s48, 0x1a000
	global_store_short v[96:97], v98, off offset:3072
	v_mul_f32_e32 v96, v123, v99
	v_mul_f32_e32 v96, v107, v96
	v_cvt_pk_bf16_f32 v98, v96, s0
	v_lshl_add_u64 v[96:97], v[128:129], 0, s[48:49]
	global_store_short v[96:97], v98, off offset:512
	v_mul_f32_e32 v96, 0xbfb8aa3b, v124
	v_exp_f32_e32 v96, v96
	v_mul_f32_e32 v97, 0xbfb8aa3b, v125
	v_exp_f32_e32 v97, v97
	s_mov_b32 s48, 0x21000
	v_add_f32_e32 v96, 1.0, v96
	v_rcp_f32_e32 v96, v96
	v_add_f32_e32 v97, 1.0, v97
	v_rcp_f32_e32 v98, v97
	v_mul_f32_e32 v96, v124, v96
	v_mul_f32_e32 v96, v108, v96
	v_cvt_pk_bf16_f32 v99, v96, s0
	v_lshl_add_u64 v[96:97], v[128:129], 0, s[48:49]
	s_mov_b32 s48, 0x22000
	global_store_short v[96:97], v99, off
	v_mul_f32_e32 v97, 0xbfb8aa3b, v126
	v_exp_f32_e32 v97, v97
	v_mul_f32_e32 v96, v125, v98
	v_mul_f32_e32 v96, v109, v96
	v_cvt_pk_bf16_f32 v98, v96, s0
	v_add_f32_e32 v96, 1.0, v97
	v_rcp_f32_e32 v99, v96
	v_lshl_add_u64 v[96:97], v[128:129], 0, s[48:49]
	s_mov_b32 s48, 0x23000
	global_store_short v[96:97], v98, off offset:1536
	v_mul_f32_e32 v97, 0xbfb8aa3b, v127
	v_exp_f32_e32 v97, v97
	v_mul_f32_e32 v96, v126, v99
	v_mul_f32_e32 v96, v110, v96
	v_cvt_pk_bf16_f32 v98, v96, s0
	v_add_f32_e32 v96, 1.0, v97
	v_rcp_f32_e32 v99, v96
	v_lshl_add_u64 v[96:97], v[128:129], 0, s[48:49]
	s_mov_b32 s48, 0x25000
	global_store_short v[96:97], v98, off offset:3072
	v_mul_f32_e32 v96, v127, v99
	v_mul_f32_e32 v96, v111, v96
	v_cvt_pk_bf16_f32 v98, v96, s0
	v_lshl_add_u64 v[96:97], v[128:129], 0, s[48:49]
	global_store_short v[96:97], v98, off offset:512
	v_mul_f32_e32 v96, 0xbfb8aa3b, v80
	v_exp_f32_e32 v96, v96
	v_mul_f32_e32 v97, 0xbfb8aa3b, v81
	v_exp_f32_e32 v97, v97
; DEV float silu(float x) { return x * sigm(x); }
; template <bool RES, class Epi>
; DEV void gemm_tile_x(const bf16_t* A0, int lda0, const bf16_t* A1, int lda1, int ksplit,
;                      const bf16_t* Bt, int ldb, int K, char* smem, const float* resb, Epi epi) {
;     ...
;       for (int r8 = 0; r8 < 8; ++r8) {
;         const int r = rh * 8 + r8;
;         const int ru = mi * 32 + (r & 3) + 8 * (r >> 2);
;         if (RES) epi(ru, rl, col, acc[mi][0][r], acc[mi][1][r], x0[r8], x1[r8]);
;         else epi(ru, rl, col, acc[mi][0][r], acc[mi][1][r], 0.f, 0.f);
;         if ((r8 & 3) == 3) __builtin_amdgcn_sched_barrier(0);
; DEV void phase_ffn_in(const Params& p, const bf16_t* wt, char* smem) {
;     ...
;               [&](int ru, int rl, int c, float v0, float v1) {
;                 (hb + ru * DFF)[(unsigned)(rl * DFF + (c >> 6) * 32 + (c & 31))] = f2bf(silu(v0) * v1);
;               });
	s_mov_b32 s48, 0x2c000
	v_add_f32_e32 v96, 1.0, v96
	v_rcp_f32_e32 v96, v96
	v_add_f32_e32 v97, 1.0, v97
	v_rcp_f32_e32 v98, v97
	v_mul_f32_e32 v80, v80, v96
	v_mul_f32_e32 v64, v64, v80
	v_mul_f32_e32 v80, 0xbfb8aa3b, v82
	v_lshl_add_u64 v[96:97], v[128:129], 0, s[48:49]
	v_exp_f32_e32 v80, v80
	v_cvt_pk_bf16_f32 v64, v64, s0
	global_store_short v[96:97], v64, off
	v_mul_f32_e32 v64, v81, v98
	v_mul_f32_e32 v64, v65, v64
	v_cvt_pk_bf16_f32 v81, v64, s0
	s_mov_b32 s48, 0x2d000
	v_add_f32_e32 v64, 1.0, v80
	v_rcp_f32_e32 v80, v64
	v_lshl_add_u64 v[64:65], v[128:129], 0, s[48:49]
	s_mov_b32 s48, 0x2e000
	global_store_short v[64:65], v81, off offset:1536
	v_mul_f32_e32 v65, 0xbfb8aa3b, v83
	v_exp_f32_e32 v65, v65
	v_mul_f32_e32 v64, v82, v80
	v_mul_f32_e32 v64, v66, v64
	v_cvt_pk_bf16_f32 v66, v64, s0
	v_add_f32_e32 v64, 1.0, v65
	v_rcp_f32_e32 v80, v64
	v_lshl_add_u64 v[64:65], v[128:129], 0, s[48:49]
	s_mov_b32 s48, 0x30000
	global_store_short v[64:65], v66, off offset:3072
	v_mul_f32_e32 v64, v83, v80
	v_mul_f32_e32 v64, v67, v64
	v_cvt_pk_bf16_f32 v66, v64, s0
	v_lshl_add_u64 v[64:65], v[128:129], 0, s[48:49]
	global_store_short v[64:65], v66, off offset:512
	v_mul_f32_e32 v64, 0xbfb8aa3b, v84
	v_exp_f32_e32 v64, v64
	v_mul_f32_e32 v65, 0xbfb8aa3b, v85
	v_exp_f32_e32 v65, v65
	s_mov_b32 s48, 0x37000
	v_add_f32_e32 v64, 1.0, v64
	v_rcp_f32_e32 v64, v64
	v_add_f32_e32 v65, 1.0, v65
	v_rcp_f32_e32 v66, v65
	v_mul_f32_e32 v64, v84, v64
	v_mul_f32_e32 v64, v68, v64
	v_cvt_pk_bf16_f32 v67, v64, s0
	v_lshl_add_u64 v[64:65], v[128:129], 0, s[48:49]
	s_mov_b32 s48, 0x38000
	global_store_short v[64:65], v67, off
	v_mul_f32_e32 v65, 0xbfb8aa3b, v86
	v_exp_f32_e32 v65, v65
	v_mul_f32_e32 v64, v85, v66
	v_mul_f32_e32 v64, v69, v64
	v_cvt_pk_bf16_f32 v66, v64, s0
	v_add_f32_e32 v64, 1.0, v65
	v_rcp_f32_e32 v67, v64
	v_lshl_add_u64 v[64:65], v[128:129], 0, s[48:49]
	s_mov_b32 s48, 0x39000
	global_store_short v[64:65], v66, off offset:1536
	v_mul_f32_e32 v65, 0xbfb8aa3b, v87
	v_exp_f32_e32 v65, v65
	v_mul_f32_e32 v64, v86, v67
	v_mul_f32_e32 v64, v70, v64
	v_cvt_pk_bf16_f32 v66, v64, s0
	v_add_f32_e32 v64, 1.0, v65
	v_rcp_f32_e32 v67, v64
	v_lshl_add_u64 v[64:65], v[128:129], 0, s[48:49]
	s_mov_b32 s48, 0x3b000
	global_store_short v[64:65], v66, off offset:3072
	v_mul_f32_e32 v64, v87, v67
	v_mul_f32_e32 v64, v71, v64
	v_cvt_pk_bf16_f32 v66, v64, s0
	v_lshl_add_u64 v[64:65], v[128:129], 0, s[48:49]
	global_store_short v[64:65], v66, off offset:512
	v_mul_f32_e32 v64, 0xbfb8aa3b, v88
	v_exp_f32_e32 v64, v64
	v_mul_f32_e32 v65, 0xbfb8aa3b, v89
	v_exp_f32_e32 v65, v65
	s_mov_b32 s48, 0x42000
	v_add_f32_e32 v64, 1.0, v64
	v_rcp_f32_e32 v64, v64
	v_add_f32_e32 v65, 1.0, v65
	v_rcp_f32_e32 v66, v65
	v_mul_f32_e32 v64, v88, v64
	v_mul_f32_e32 v64, v72, v64
	v_cvt_pk_bf16_f32 v67, v64, s0
	v_lshl_add_u64 v[64:65], v[128:129], 0, s[48:49]
	s_mov_b32 s48, 0x43000
	global_store_short v[64:65], v67, off
	v_mul_f32_e32 v65, 0xbfb8aa3b, v90
	v_exp_f32_e32 v65, v65
	v_mul_f32_e32 v64, v89, v66
	v_mul_f32_e32 v64, v73, v64
	v_cvt_pk_bf16_f32 v66, v64, s0
	v_add_f32_e32 v64, 1.0, v65
	v_rcp_f32_e32 v67, v64
	v_lshl_add_u64 v[64:65], v[128:129], 0, s[48:49]
	s_mov_b32 s48, 0x44000
	global_store_short v[64:65], v66, off offset:1536
	v_mul_f32_e32 v65, 0xbfb8aa3b, v91
	v_exp_f32_e32 v65, v65
	v_mul_f32_e32 v64, v90, v67
	v_mul_f32_e32 v64, v74, v64
	v_cvt_pk_bf16_f32 v66, v64, s0
	v_add_f32_e32 v64, 1.0, v65
	v_rcp_f32_e32 v67, v64
	v_lshl_add_u64 v[64:65], v[128:129], 0, s[48:49]
	s_mov_b32 s48, 0x46000
	global_store_short v[64:65], v66, off offset:3072
	v_mul_f32_e32 v64, v91, v67
	v_mul_f32_e32 v64, v75, v64
	v_cvt_pk_bf16_f32 v66, v64, s0
	v_lshl_add_u64 v[64:65], v[128:129], 0, s[48:49]
	global_store_short v[64:65], v66, off offset:512
	v_mul_f32_e32 v64, 0xbfb8aa3b, v92
	v_exp_f32_e32 v64, v64
	v_mul_f32_e32 v65, 0xbfb8aa3b, v93
	v_exp_f32_e32 v65, v65
	s_mov_b32 s48, 0x4d000
	v_add_f32_e32 v64, 1.0, v64
	v_rcp_f32_e32 v64, v64
	v_add_f32_e32 v65, 1.0, v65
	v_rcp_f32_e32 v66, v65
	v_mul_f32_e32 v64, v92, v64
	v_mul_f32_e32 v64, v76, v64
	v_cvt_pk_bf16_f32 v67, v64, s0
	v_lshl_add_u64 v[64:65], v[128:129], 0, s[48:49]
	s_mov_b32 s48, 0x4e000
	global_store_short v[64:65], v67, off
	v_mul_f32_e32 v65, 0xbfb8aa3b, v94
	v_exp_f32_e32 v65, v65
	v_mul_f32_e32 v64, v93, v66
	v_mul_f32_e32 v64, v77, v64
	v_cvt_pk_bf16_f32 v66, v64, s0
	v_add_f32_e32 v64, 1.0, v65
	v_rcp_f32_e32 v67, v64
	v_lshl_add_u64 v[64:65], v[128:129], 0, s[48:49]
	s_mov_b32 s48, 0x4f000
	global_store_short v[64:65], v66, off offset:1536
	v_mul_f32_e32 v65, 0xbfb8aa3b, v95
	v_exp_f32_e32 v65, v65
	v_mul_f32_e32 v64, v94, v67
	v_mul_f32_e32 v64, v78, v64
	v_cvt_pk_bf16_f32 v66, v64, s0
	v_add_f32_e32 v64, 1.0, v65
	v_rcp_f32_e32 v67, v64
	v_lshl_add_u64 v[64:65], v[128:129], 0, s[48:49]
	s_mov_b32 s48, 0x51000
	global_store_short v[64:65], v66, off offset:3072
	v_mul_f32_e32 v64, v95, v67
	v_mul_f32_e32 v64, v79, v64
	v_cvt_pk_bf16_f32 v66, v64, s0
	v_lshl_add_u64 v[64:65], v[128:129], 0, s[48:49]
	global_store_short v[64:65], v66, off offset:512
	v_mul_f32_e32 v64, 0xbfb8aa3b, v48
	v_exp_f32_e32 v64, v64
	v_mul_f32_e32 v65, 0xbfb8aa3b, v49
	v_exp_f32_e32 v65, v65
	s_mov_b32 s48, 0x58000
	v_add_f32_e32 v64, 1.0, v64
	v_rcp_f32_e32 v64, v64
	v_add_f32_e32 v65, 1.0, v65
	v_rcp_f32_e32 v66, v65
	v_mul_f32_e32 v48, v48, v64
	v_mul_f32_e32 v32, v32, v48
	v_mul_f32_e32 v48, 0xbfb8aa3b, v50
	v_lshl_add_u64 v[64:65], v[128:129], 0, s[48:49]
	v_exp_f32_e32 v48, v48
	v_cvt_pk_bf16_f32 v32, v32, s0
	global_store_short v[64:65], v32, off
	v_mul_f32_e32 v32, v49, v66
	v_mul_f32_e32 v32, v33, v32
	v_cvt_pk_bf16_f32 v49, v32, s0
; DEV float silu(float x) { return x * sigm(x); }
; template <bool RES, class Epi>
; DEV void gemm_tile_x(const bf16_t* A0, int lda0, const bf16_t* A1, int lda1, int ksplit,
;                      const bf16_t* Bt, int ldb, int K, char* smem, const float* resb, Epi epi) {
;     ...
;       for (int r8 = 0; r8 < 8; ++r8) {
;         const int r = rh * 8 + r8;
;         const int ru = mi * 32 + (r & 3) + 8 * (r >> 2);
;         if (RES) epi(ru, rl, col, acc[mi][0][r], acc[mi][1][r], x0[r8], x1[r8]);
;         else epi(ru, rl, col, acc[mi][0][r], acc[mi][1][r], 0.f, 0.f);
;         if ((r8 & 3) == 3) __builtin_amdgcn_sched_barrier(0);
; DEV void phase_ffn_in(const Params& p, const bf16_t* wt, char* smem) {
;     ...
;               [&](int ru, int rl, int c, float v0, float v1) {
;                 (hb + ru * DFF)[(unsigned)(rl * DFF + (c >> 6) * 32 + (c & 31))] = f2bf(silu(v0) * v1);
;               });
	s_mov_b32 s48, 0x59000
	v_add_f32_e32 v32, 1.0, v48
	v_rcp_f32_e32 v48, v32
	v_lshl_add_u64 v[32:33], v[128:129], 0, s[48:49]
	s_mov_b32 s48, 0x5a000
	global_store_short v[32:33], v49, off offset:1536
	v_mul_f32_e32 v33, 0xbfb8aa3b, v51
	v_exp_f32_e32 v33, v33
	v_mul_f32_e32 v32, v50, v48
	v_mul_f32_e32 v32, v34, v32
	v_cvt_pk_bf16_f32 v34, v32, s0
	v_add_f32_e32 v32, 1.0, v33
	v_rcp_f32_e32 v48, v32
	v_lshl_add_u64 v[32:33], v[128:129], 0, s[48:49]
	s_mov_b32 s48, 0x5c000
	global_store_short v[32:33], v34, off offset:3072
	v_mul_f32_e32 v32, v51, v48
	v_mul_f32_e32 v32, v35, v32
	v_cvt_pk_bf16_f32 v34, v32, s0
	v_lshl_add_u64 v[32:33], v[128:129], 0, s[48:49]
	global_store_short v[32:33], v34, off offset:512
	v_mul_f32_e32 v32, 0xbfb8aa3b, v52
	v_exp_f32_e32 v32, v32
	v_mul_f32_e32 v33, 0xbfb8aa3b, v53
	v_exp_f32_e32 v33, v33
	s_mov_b32 s48, 0x63000
	v_add_f32_e32 v32, 1.0, v32
	v_rcp_f32_e32 v32, v32
	v_add_f32_e32 v33, 1.0, v33
	v_rcp_f32_e32 v34, v33
	v_mul_f32_e32 v32, v52, v32
	v_mul_f32_e32 v32, v36, v32
	v_cvt_pk_bf16_f32 v35, v32, s0
	v_lshl_add_u64 v[32:33], v[128:129], 0, s[48:49]
	s_mov_b32 s48, 0x64000
	global_store_short v[32:33], v35, off
	v_mul_f32_e32 v33, 0xbfb8aa3b, v54
	v_exp_f32_e32 v33, v33
	v_mul_f32_e32 v32, v53, v34
	v_mul_f32_e32 v32, v37, v32
	v_cvt_pk_bf16_f32 v34, v32, s0
	v_add_f32_e32 v32, 1.0, v33
	v_rcp_f32_e32 v35, v32
	v_lshl_add_u64 v[32:33], v[128:129], 0, s[48:49]
	s_mov_b32 s48, 0x65000
	global_store_short v[32:33], v34, off offset:1536
	v_mul_f32_e32 v33, 0xbfb8aa3b, v55
	v_exp_f32_e32 v33, v33
	v_mul_f32_e32 v32, v54, v35
	v_mul_f32_e32 v32, v38, v32
	v_cvt_pk_bf16_f32 v34, v32, s0
	v_add_f32_e32 v32, 1.0, v33
	v_rcp_f32_e32 v35, v32
	v_lshl_add_u64 v[32:33], v[128:129], 0, s[48:49]
	s_mov_b32 s48, 0x67000
	global_store_short v[32:33], v34, off offset:3072
	v_mul_f32_e32 v32, v55, v35
	v_mul_f32_e32 v32, v39, v32
	v_cvt_pk_bf16_f32 v34, v32, s0
	v_lshl_add_u64 v[32:33], v[128:129], 0, s[48:49]
	global_store_short v[32:33], v34, off offset:512
	v_mul_f32_e32 v32, 0xbfb8aa3b, v56
	v_exp_f32_e32 v32, v32
	v_mul_f32_e32 v33, 0xbfb8aa3b, v57
	v_exp_f32_e32 v33, v33
	s_mov_b32 s48, 0x6e000
	v_add_f32_e32 v32, 1.0, v32
	v_rcp_f32_e32 v32, v32
	v_add_f32_e32 v33, 1.0, v33
	v_rcp_f32_e32 v34, v33
	v_mul_f32_e32 v32, v56, v32
	v_mul_f32_e32 v32, v40, v32
	v_cvt_pk_bf16_f32 v35, v32, s0
	v_lshl_add_u64 v[32:33], v[128:129], 0, s[48:49]
	s_mov_b32 s48, 0x6f000
	global_store_short v[32:33], v35, off
	v_mul_f32_e32 v33, 0xbfb8aa3b, v58
	v_exp_f32_e32 v33, v33
	v_mul_f32_e32 v32, v57, v34
	v_mul_f32_e32 v32, v41, v32
	v_cvt_pk_bf16_f32 v34, v32, s0
	v_add_f32_e32 v32, 1.0, v33
	v_rcp_f32_e32 v35, v32
	v_lshl_add_u64 v[32:33], v[128:129], 0, s[48:49]
	s_mov_b32 s48, 0x70000
	global_store_short v[32:33], v34, off offset:1536
	v_mul_f32_e32 v33, 0xbfb8aa3b, v59
	v_exp_f32_e32 v33, v33
	v_mul_f32_e32 v32, v58, v35
	v_mul_f32_e32 v32, v42, v32
	v_cvt_pk_bf16_f32 v34, v32, s0
	v_add_f32_e32 v32, 1.0, v33
	v_rcp_f32_e32 v35, v32
	v_lshl_add_u64 v[32:33], v[128:129], 0, s[48:49]
	s_mov_b32 s48, 0x72000
	global_store_short v[32:33], v34, off offset:3072
	v_mul_f32_e32 v32, v59, v35
	v_mul_f32_e32 v32, v43, v32
	v_cvt_pk_bf16_f32 v34, v32, s0
	v_lshl_add_u64 v[32:33], v[128:129], 0, s[48:49]
	global_store_short v[32:33], v34, off offset:512
	v_mul_f32_e32 v32, 0xbfb8aa3b, v60
	v_exp_f32_e32 v32, v32
	v_mul_f32_e32 v33, 0xbfb8aa3b, v61
	v_exp_f32_e32 v33, v33
	s_mov_b32 s48, 0x79000
	v_add_f32_e32 v32, 1.0, v32
	v_rcp_f32_e32 v32, v32
	v_add_f32_e32 v33, 1.0, v33
	v_rcp_f32_e32 v34, v33
	v_mul_f32_e32 v32, v60, v32
	v_mul_f32_e32 v32, v44, v32
	v_cvt_pk_bf16_f32 v35, v32, s0
	v_lshl_add_u64 v[32:33], v[128:129], 0, s[48:49]
	s_mov_b32 s48, 0x7a000
	global_store_short v[32:33], v35, off
	v_mul_f32_e32 v33, 0xbfb8aa3b, v62
	v_exp_f32_e32 v33, v33
	v_mul_f32_e32 v32, v61, v34
	v_mul_f32_e32 v32, v45, v32
	v_cvt_pk_bf16_f32 v34, v32, s0
	v_add_f32_e32 v32, 1.0, v33
	v_rcp_f32_e32 v35, v32
	v_lshl_add_u64 v[32:33], v[128:129], 0, s[48:49]
	s_mov_b32 s48, 0x7b000
	global_store_short v[32:33], v34, off offset:1536
	v_mul_f32_e32 v33, 0xbfb8aa3b, v63
	v_exp_f32_e32 v33, v33
	v_mul_f32_e32 v32, v62, v35
	v_mul_f32_e32 v32, v46, v32
	v_cvt_pk_bf16_f32 v34, v32, s0
	v_add_f32_e32 v32, 1.0, v33
	v_rcp_f32_e32 v35, v32
	v_lshl_add_u64 v[32:33], v[128:129], 0, s[48:49]
	s_mov_b32 s48, 0x7d000
	global_store_short v[32:33], v34, off offset:3072
	v_mul_f32_e32 v32, v63, v35
	v_mul_f32_e32 v32, v47, v32
	v_cvt_pk_bf16_f32 v34, v32, s0
	v_lshl_add_u64 v[32:33], v[128:129], 0, s[48:49]
	global_store_short v[32:33], v34, off offset:512
	v_mul_f32_e32 v32, 0xbfb8aa3b, v16
	v_exp_f32_e32 v32, v32
	v_mul_f32_e32 v33, 0xbfb8aa3b, v17
	v_exp_f32_e32 v33, v33
	s_mov_b32 s48, 0x84000
	v_add_f32_e32 v32, 1.0, v32
	v_rcp_f32_e32 v32, v32
	v_add_f32_e32 v33, 1.0, v33
	v_rcp_f32_e32 v34, v33
	v_mul_f32_e32 v16, v16, v32
; DEV float silu(float x) { return x * sigm(x); }
; template <bool RES, class Epi>
; DEV void gemm_tile_x(const bf16_t* A0, int lda0, const bf16_t* A1, int lda1, int ksplit,
;                      const bf16_t* Bt, int ldb, int K, char* smem, const float* resb, Epi epi) {
;     ...
;   for (int mi = 0; mi < 4; ++mi) {
; #pragma unroll
;     for (int rh = 0; rh < 2; ++rh) {
;       float x0[8], x1[8];
;       if (RES) {
; #pragma unroll
;         for (int r8 = 0; r8 < 8; ++r8) {
;           const int r = rh * 8 + r8;
;           const int ru = mi * 32 + (r & 3) + 8 * (r >> 2);
;           const float* rp = resb + ru * DM;
;           x0[r8] = rp[resoff];
;           x1[r8] = rp[resoff + 32];
;         }
;       }
; #pragma unroll
;       for (int r8 = 0; r8 < 8; ++r8) {
;         const int r = rh * 8 + r8;
;         const int ru = mi * 32 + (r & 3) + 8 * (r >> 2);
;         if (RES) epi(ru, rl, col, acc[mi][0][r], acc[mi][1][r], x0[r8], x1[r8]);
;         else epi(ru, rl, col, acc[mi][0][r], acc[mi][1][r], 0.f, 0.f);
;         if ((r8 & 3) == 3) __builtin_amdgcn_sched_barrier(0);
;       }
; DEV void phase_ffn_in(const Params& p, const bf16_t* wt, char* smem) {
;     ...
;               [&](int ru, int rl, int c, float v0, float v1) {
;                 (hb + ru * DFF)[(unsigned)(rl * DFF + (c >> 6) * 32 + (c & 31))] = f2bf(silu(v0) * v1);
;               });
	v_mul_f32_e32 v0, v0, v16
	v_mul_f32_e32 v16, 0xbfb8aa3b, v18
	v_lshl_add_u64 v[32:33], v[128:129], 0, s[48:49]
	v_exp_f32_e32 v16, v16
	v_cvt_pk_bf16_f32 v0, v0, s0
	global_store_short v[32:33], v0, off
	v_mul_f32_e32 v0, v17, v34
	v_mul_f32_e32 v0, v1, v0
	v_cvt_pk_bf16_f32 v17, v0, s0
	s_mov_b32 s48, 0x85000
	v_add_f32_e32 v0, 1.0, v16
	v_rcp_f32_e32 v16, v0
	v_lshl_add_u64 v[0:1], v[128:129], 0, s[48:49]
	s_mov_b32 s48, 0x86000
	global_store_short v[0:1], v17, off offset:1536
	v_mul_f32_e32 v1, 0xbfb8aa3b, v19
	v_exp_f32_e32 v1, v1
	v_mul_f32_e32 v0, v18, v16
	v_mul_f32_e32 v0, v2, v0
	v_cvt_pk_bf16_f32 v2, v0, s0
	v_add_f32_e32 v0, 1.0, v1
	v_rcp_f32_e32 v16, v0
	v_lshl_add_u64 v[0:1], v[128:129], 0, s[48:49]
	s_mov_b32 s48, 0x88000
	global_store_short v[0:1], v2, off offset:3072
	v_mul_f32_e32 v0, v19, v16
	v_mul_f32_e32 v0, v3, v0
	v_cvt_pk_bf16_f32 v2, v0, s0
	v_lshl_add_u64 v[0:1], v[128:129], 0, s[48:49]
	global_store_short v[0:1], v2, off offset:512
	v_mul_f32_e32 v0, 0xbfb8aa3b, v20
	v_exp_f32_e32 v0, v0
	v_mul_f32_e32 v1, 0xbfb8aa3b, v21
	v_exp_f32_e32 v1, v1
	s_mov_b32 s48, 0x8f000
	v_add_f32_e32 v0, 1.0, v0
	v_rcp_f32_e32 v0, v0
	v_add_f32_e32 v1, 1.0, v1
	v_rcp_f32_e32 v2, v1
	v_mul_f32_e32 v0, v20, v0
	v_mul_f32_e32 v0, v4, v0
	v_cvt_pk_bf16_f32 v3, v0, s0
	v_lshl_add_u64 v[0:1], v[128:129], 0, s[48:49]
	s_mov_b32 s48, 0x90000
	global_store_short v[0:1], v3, off
	v_mul_f32_e32 v1, 0xbfb8aa3b, v22
	v_exp_f32_e32 v1, v1
	v_mul_f32_e32 v0, v21, v2
	v_mul_f32_e32 v0, v5, v0
	v_cvt_pk_bf16_f32 v2, v0, s0
	v_add_f32_e32 v0, 1.0, v1
	v_rcp_f32_e32 v3, v0
	v_lshl_add_u64 v[0:1], v[128:129], 0, s[48:49]
	s_mov_b32 s48, 0x91000
	global_store_short v[0:1], v2, off offset:1536
	v_mul_f32_e32 v1, 0xbfb8aa3b, v23
	v_exp_f32_e32 v1, v1
	v_mul_f32_e32 v0, v22, v3
	v_mul_f32_e32 v0, v6, v0
	v_cvt_pk_bf16_f32 v2, v0, s0
	v_add_f32_e32 v0, 1.0, v1
	v_rcp_f32_e32 v3, v0
	v_lshl_add_u64 v[0:1], v[128:129], 0, s[48:49]
	s_mov_b32 s48, 0x93000
	global_store_short v[0:1], v2, off offset:3072
	v_mul_f32_e32 v0, v23, v3
	v_mul_f32_e32 v0, v7, v0
	v_cvt_pk_bf16_f32 v2, v0, s0
	v_lshl_add_u64 v[0:1], v[128:129], 0, s[48:49]
	global_store_short v[0:1], v2, off offset:512
	v_mul_f32_e32 v0, 0xbfb8aa3b, v24
	v_exp_f32_e32 v0, v0
	v_mul_f32_e32 v1, 0xbfb8aa3b, v25
	v_exp_f32_e32 v1, v1
	s_mov_b32 s48, 0x9a000
	v_add_f32_e32 v0, 1.0, v0
	v_rcp_f32_e32 v0, v0
	v_add_f32_e32 v1, 1.0, v1
	v_rcp_f32_e32 v2, v1
	v_mul_f32_e32 v0, v24, v0
	v_mul_f32_e32 v0, v8, v0
	v_cvt_pk_bf16_f32 v3, v0, s0
	v_lshl_add_u64 v[0:1], v[128:129], 0, s[48:49]
	s_mov_b32 s48, 0x9b000
	global_store_short v[0:1], v3, off
	v_mul_f32_e32 v0, v25, v2
	v_mul_f32_e32 v0, v9, v0
	v_cvt_pk_bf16_f32 v2, v0, s0
	v_mul_f32_e32 v0, 0xbfb8aa3b, v26
	v_exp_f32_e32 v3, v0
	v_lshl_add_u64 v[0:1], v[128:129], 0, s[48:49]
	v_add_f32_e32 v3, 1.0, v3
	s_nop 0
	global_store_short v[0:1], v2, off offset:1536
	v_mul_f32_e32 v0, 0xbfb8aa3b, v27
	v_exp_f32_e32 v0, v0
	v_rcp_f32_e32 v3, v3
	v_add_f32_e32 v0, 1.0, v0
	v_mul_f32_e32 v1, v26, v3
	v_rcp_f32_e32 v3, v0
	v_mul_f32_e32 v1, v10, v1
	v_add_co_u32_e32 v0, vcc, s78, v128
	v_cvt_pk_bf16_f32 v2, v1, s0
	s_nop 0
	v_addc_co_u32_e32 v1, vcc, 0, v129, vcc
	global_store_short v[0:1], v2, off offset:3072
	v_mul_f32_e32 v0, v27, v3
	v_mul_f32_e32 v0, v11, v0
	v_cvt_pk_bf16_f32 v2, v0, s0
	v_add_co_u32_e32 v0, vcc, s79, v128
	s_nop 1
	v_addc_co_u32_e32 v1, vcc, 0, v129, vcc
	global_store_short v[0:1], v2, off offset:512
	v_mul_f32_e32 v0, 0xbfb8aa3b, v28
	v_exp_f32_e32 v0, v0
	v_mul_f32_e32 v3, 0xbfb8aa3b, v29
	v_exp_f32_e32 v3, v3
	v_add_f32_e32 v0, 1.0, v0
	v_rcp_f32_e32 v2, v0
	v_add_co_u32_e32 v0, vcc, s80, v128
	v_add_f32_e32 v3, 1.0, v3
	v_mul_f32_e32 v2, v28, v2
	v_mul_f32_e32 v2, v12, v2
	v_addc_co_u32_e32 v1, vcc, 0, v129, vcc
	v_cvt_pk_bf16_f32 v2, v2, s0
	global_store_short v[0:1], v2, off
	v_mul_f32_e32 v0, 0xbfb8aa3b, v30
	v_rcp_f32_e32 v3, v3
	v_exp_f32_e32 v0, v0
	v_mul_f32_e32 v1, v29, v3
	v_add_f32_e32 v0, 1.0, v0
	v_mul_f32_e32 v1, v13, v1
	v_rcp_f32_e32 v3, v0
	v_add_co_u32_e32 v0, vcc, s81, v128
	v_cvt_pk_bf16_f32 v2, v1, s0
	s_nop 0
	v_addc_co_u32_e32 v1, vcc, 0, v129, vcc
	global_store_short v[0:1], v2, off offset:1536
	v_mul_f32_e32 v1, 0xbfb8aa3b, v31
	v_exp_f32_e32 v1, v1
	v_mul_f32_e32 v0, v30, v3
	v_mul_f32_e32 v0, v14, v0
	v_cvt_pk_bf16_f32 v2, v0, s0
	v_add_f32_e32 v1, 1.0, v1
	v_rcp_f32_e32 v3, v1
	v_add_co_u32_e32 v0, vcc, s82, v128
	s_nop 1
	v_addc_co_u32_e32 v1, vcc, 0, v129, vcc
	global_store_short v[0:1], v2, off offset:3072
	v_mul_f32_e32 v0, v31, v3
	v_mul_f32_e32 v0, v15, v0
	v_cvt_pk_bf16_f32 v2, v0, s0
	v_add_co_u32_e32 v0, vcc, 0xa9000, v128
	s_nop 1
	v_addc_co_u32_e32 v1, vcc, 0, v129, vcc
	global_store_short v[0:1], v2, off offset:512
	s_add_i32 s58, s58, 1
	s_mul_i32 s48, s58, s72
	s_add_i32 s48, s48, s73
	s_cmpk_lt_u32 s48, 0x420
	s_cbranch_scc0 .LBB0_3209
